# P7: first K-tile counted waits of a unit no longer wait for the previous unit's 8 epilogue stores (vmcnt 18 / 10 by flag), on top of v144
# baseline (speedup 1.0000x reference)
.LBB0_306:
	s_waitcnt vmcnt(0)
	v_bfe_u32 v144, v18, 4, 2
	v_and_b32_e32 v1, 15, v18
	v_lshlrev_b32_e32 v19, 4, v144
	v_lshlrev_b32_e32 v18, 2, v18
	s_and_b32 s19, s16, 3
	v_lshl_or_b32 v19, v1, 6, v19
	s_lshl_b32 s16, s22, 13
	v_and_b32_e32 v18, 32, v18
	s_add_i32 m0, s45, 0x18000
	v_lshl_add_u64 v[10:11], v[10:11], 0, s[96:97]
	s_lshl_b32 s49, s22, 6
	v_bitop3_b32 v20, v19, s16, v18 bitop3:0xde
	s_lshl_b32 s50, s19, 5
	s_lshl_b32 s16, s19, 12
	global_load_lds_dwordx4 v[10:11], off
	v_lshl_add_u64 v[8:9], v[8:9], 0, s[96:97]
	s_add_i32 m0, s45, 0x1a000
	s_add_i32 s51, s45, 0x8000
	s_add_i32 s52, s45, 0xa000
	v_bitop3_b32 v145, v19, s16, v18 bitop3:0xde
	global_load_lds_dwordx4 v[8:9], off
	v_lshl_add_u64 v[4:5], v[4:5], 0, s[96:97]
	s_mov_b32 m0, s51
	s_add_u32 s16, s30, 0x40080
	global_load_lds_dwordx4 v[4:5], off
	v_lshl_add_u64 v[4:5], v[6:7], 0, s[96:97]
	s_mov_b32 m0, s52
	s_addc_u32 s17, s31, 0
	global_load_lds_dwordx4 v[4:5], off
	s_add_i32 m0, s45, 0x1c000
	v_lshl_add_u64 v[4:5], s[16:17], 0, v[2:3]
	global_load_lds_dwordx4 v[4:5], off
	v_lshl_add_u64 v[4:5], s[16:17], 0, v[132:133]
	s_add_i32 m0, s45, 0x1e000
	s_cmpk_lt_u32 s18, 0x100
	global_load_lds_dwordx4 v[4:5], off
	v_lshlrev_b32_e32 v4, 14, v16
	v_and_b32_e32 v4, 0xffff8000, v4
	s_cselect_b64 s[16:17], -1, 0
	s_and_b32 s18, s18, 0xffffff00
	s_lshl_b32 s19, s19, 6
	v_lshl_add_u32 v4, v15, 11, v4
	v_and_b32_e32 v5, 1, v16
	s_or_b32 s53, s19, s18
	v_lshl_or_b32 v4, v5, 6, v4
	s_add_u32 s18, s6, 0x380000
	v_lshl_add_u32 v138, v17, 1, v4
	v_lshlrev_b32_e32 v4, 14, v12
	s_addc_u32 s19, s7, 0
	v_and_b32_e32 v4, 0xffff8000, v4
	s_waitcnt vmcnt(8)
	s_barrier
	s_waitcnt vmcnt(6)
	s_add_u32 s20, s6, 0x4700000
	v_lshl_add_u32 v4, v13, 11, v4
	v_and_b32_e32 v5, 1, v12
	s_addc_u32 s21, s7, 0
	s_lshl_b32 s54, s22, 8
	v_lshl_or_b32 v4, v5, 6, v4
	v_readlane_b32 s22, v253, 60
	s_add_i32 s54, s54, 0x20000
	v_mov_b32_e32 v139, v3
	v_lshl_add_u32 v140, v14, 1, v4
	v_mov_b32_e32 v141, v3
	s_mov_b32 s55, 0
	v_add_u32_e32 v146, 0, v20
	v_readlane_b32 s56, v253, 57
	s_mov_b32 s57, s22
	s_barrier
	v_readlane_b32 s23, v253, 61
	v_writelane_b32 v255, 0, 61
	s_branch .LBB0_309

.Lk7_peel:
	s_add_u32 s30, s28, 0xfffc0080
	s_addc_u32 s31, s29, -1
	s_add_i32 s63, 0, 0x10000
	s_cmp_eq_u32 s62, 12
	s_cselect_b32 s35, s25, s31
	s_cselect_b32 s34, s58, s30
	v_add_u32_e32 v142, s63, v145
	s_cselect_b32 s31, s23, s61
	s_cselect_b32 s30, s59, s60
	s_add_i32 s66, 0, 0x14000
	ds_read_b128 v[148:151], v142
	ds_read_b128 v[152:155], v142 offset:1024
	ds_read_b128 v[156:159], v142 offset:2048
	ds_read_b128 v[160:163], v142 offset:3072
	v_add_u32_e32 v142, s66, v145
	ds_read_b128 v[164:167], v142
	ds_read_b128 v[168:171], v142 offset:1024
	ds_read_b128 v[172:175], v142 offset:2048
	ds_read_b128 v[176:179], v142 offset:3072
	v_lshl_add_u64 v[142:143], s[28:29], 0, v[138:139]
	s_add_i32 m0, s45, 0xc000
	ds_read_b128 v[180:183], v146
	ds_read_b128 v[184:187], v146 offset:1024
	ds_read_b128 v[188:191], v146 offset:2048
	ds_read_b128 v[192:195], v146 offset:3072
	ds_read_b128 v[206:209], v146 offset:4096
	ds_read_b128 v[210:213], v146 offset:5120
	ds_read_b128 v[214:217], v146 offset:6144
	ds_read_b128 v[218:221], v146 offset:7168
	global_load_lds_dwordx4 v[142:143], off
	v_lshl_add_u64 v[142:143], s[28:29], 0, v[140:141]
	s_add_i32 m0, s45, 0xe000
	s_nop 0
	global_load_lds_dwordx4 v[142:143], off
	v_readlane_b32 s101, v255, 61
	s_nop 3
	s_cmp_eq_u32 s101, 1
	s_cbranch_scc1 .Lk7_w18b
	s_waitcnt vmcnt(10)
	s_branch .Lk7_wjb
.Lk7_w18b:
	s_waitcnt vmcnt(18)
.Lk7_wjb:
	s_waitcnt lgkmcnt(0)
	s_barrier
	s_waitcnt lgkmcnt(0)
	v_mfma_f32_16x16x32_bf16 v[128:131], v[148:151], v[180:183], 0
	v_mfma_f32_16x16x32_bf16 v[120:123], v[156:159], v[180:183], 0
	v_mfma_f32_16x16x32_bf16 v[112:115], v[148:151], v[188:191], 0
	v_mfma_f32_16x16x32_bf16 v[104:107], v[156:159], v[188:191], 0
	v_mfma_f32_16x16x32_bf16 v[96:99], v[148:151], v[206:209], 0
	v_mfma_f32_16x16x32_bf16 v[88:91], v[156:159], v[206:209], 0
	v_mfma_f32_16x16x32_bf16 v[80:83], v[148:151], v[214:217], 0
	v_mfma_f32_16x16x32_bf16 v[72:75], v[156:159], v[214:217], 0
	v_mfma_f32_16x16x32_bf16 v[128:131], v[152:155], v[184:187], v[128:131]
	v_mfma_f32_16x16x32_bf16 v[120:123], v[160:163], v[184:187], v[120:123]
	v_mfma_f32_16x16x32_bf16 v[112:115], v[152:155], v[192:195], v[112:115]
	v_mfma_f32_16x16x32_bf16 v[104:107], v[160:163], v[192:195], v[104:107]
	v_mfma_f32_16x16x32_bf16 v[96:99], v[152:155], v[210:213], v[96:99]
	v_mfma_f32_16x16x32_bf16 v[88:91], v[160:163], v[210:213], v[88:91]
	v_mfma_f32_16x16x32_bf16 v[80:83], v[152:155], v[218:221], v[80:83]
	v_mfma_f32_16x16x32_bf16 v[72:75], v[160:163], v[218:221], v[72:75]
	v_mfma_f32_16x16x32_bf16 v[124:127], v[164:167], v[180:183], 0
	v_mfma_f32_16x16x32_bf16 v[116:119], v[172:175], v[180:183], 0
	v_mfma_f32_16x16x32_bf16 v[108:111], v[164:167], v[188:191], 0
	v_mfma_f32_16x16x32_bf16 v[100:103], v[172:175], v[188:191], 0
	v_mfma_f32_16x16x32_bf16 v[92:95], v[164:167], v[206:209], 0
	v_mfma_f32_16x16x32_bf16 v[84:87], v[172:175], v[206:209], 0
	v_mfma_f32_16x16x32_bf16 v[76:79], v[164:167], v[214:217], 0
	v_mfma_f32_16x16x32_bf16 v[68:71], v[172:175], v[214:217], 0
	v_mfma_f32_16x16x32_bf16 v[124:127], v[168:171], v[184:187], v[124:127]
	v_mfma_f32_16x16x32_bf16 v[116:119], v[176:179], v[184:187], v[116:119]
	v_mfma_f32_16x16x32_bf16 v[108:111], v[168:171], v[192:195], v[108:111]
	v_mfma_f32_16x16x32_bf16 v[100:103], v[176:179], v[192:195], v[100:103]
	v_mfma_f32_16x16x32_bf16 v[92:95], v[168:171], v[210:213], v[92:95]
	v_mfma_f32_16x16x32_bf16 v[84:87], v[176:179], v[210:213], v[84:87]
	v_mfma_f32_16x16x32_bf16 v[76:79], v[168:171], v[218:221], v[76:79]
	v_mfma_f32_16x16x32_bf16 v[68:71], v[176:179], v[218:221], v[68:71]
	s_barrier
	s_add_i32 s63, s63, s36
	v_lshl_add_u64 v[142:143], s[30:31], 0, v[2:3]
	s_mov_b32 m0, s63
	ds_read_b128 v[180:183], v146 offset:16384
	ds_read_b128 v[184:187], v146 offset:17408
	ds_read_b128 v[188:191], v146 offset:18432
	ds_read_b128 v[192:195], v146 offset:19456
	ds_read_b128 v[206:209], v146 offset:20480
	ds_read_b128 v[210:213], v146 offset:21504
	ds_read_b128 v[214:217], v146 offset:22528
	ds_read_b128 v[218:221], v146 offset:23552
	global_load_lds_dwordx4 v[142:143], off
	s_add_i32 m0, s63, 0x2000
	s_add_u32 s64, s30, 0x40000
	v_lshl_add_u64 v[236:237], s[30:31], 0, v[132:133]
	s_addc_u32 s65, s31, 0
	s_add_i32 s63, s66, s36
	global_load_lds_dwordx4 v[236:237], off
	v_lshl_add_u64 v[238:239], s[64:65], 0, v[2:3]
	s_mov_b32 m0, s63
	v_lshl_add_u64 v[240:241], s[34:35], 0, v[134:135]
	global_load_lds_dwordx4 v[238:239], off
	v_lshl_add_u64 v[238:239], s[64:65], 0, v[132:133]
	s_add_i32 m0, s63, 0x2000
	s_nop 0
	global_load_lds_dwordx4 v[238:239], off
	v_lshl_add_u64 v[238:239], s[34:35], 0, v[136:137]
	s_mov_b32 m0, s45
	s_nop 0
	global_load_lds_dwordx4 v[238:239], off
	s_mov_b32 m0, s46
	s_nop 0
	global_load_lds_dwordx4 v[240:241], off
	s_add_i32 s55, s55, 1
	s_mul_i32 s23, s55, s84
	s_mul_hi_u32 s25, s55, s83
	s_add_i32 s25, s25, s23
	s_mul_i32 s23, s55, s83
	s_add_u32 s100, s23, s2
	s_addc_u32 s101, s25, s93
	v_cmp_gt_i64_e32 vcc, s[100:101], v[202:203]
	v_cmp_lt_i64_e64 s[38:39], s[100:101], v[200:201]
	s_cbranch_vccnz .Lm7_nonext
	s_and_b32 s25, s100, 7
	s_lshr_b32 s23, s100, 3
	s_mul_i32 s101, s25, 0xb3
	s_sub_i32 s100, s25, 6
	s_max_i32 s100, s100, 0
	s_sub_i32 s101, s101, s100
	s_add_i32 s23, s23, s101
	s_mul_hi_i32 s25, s23, 0x2e8ba2e9
	s_ashr_i32 s25, s25, 3
	s_mul_i32 s101, s25, 44
	s_sub_i32 s23, s23, s101
	s_lshl_b32 s25, s25, 1
	s_sub_i32 s101, 0x41, s25
	s_min_i32 s101, s101, 2
	s_sub_i32 s101, s101, 1
	s_lshr_b32 s22, s23, s101
	s_and_b32 s23, s23, s101
	s_add_i32 s24, s25, s23
.Lm7_nonext:
	s_lshl_b32 s100, s24, 19
	s_add_u32 s26, s37, s100
	s_addc_u32 s27, s44, 0
	s_and_b64 s[100:101], s[38:39], exec
	s_cselect_b32 s25, s27, s29
	s_cselect_b32 s58, s26, s28
	s_lshl_b32 s100, s22, 19
	s_add_u32 s42, s40, s100
	s_addc_u32 s43, s41, 0
	s_and_b64 s[100:101], s[38:39], exec
	s_cselect_b32 s23, s43, s61
	s_cselect_b32 s59, s42, s60
	v_readlane_b32 s101, v255, 61
	s_nop 3
	s_cmp_eq_u32 s101, 1
	s_cbranch_scc1 .Lk7_w18a
	s_waitcnt vmcnt(10)
	s_branch .Lk7_wja

.Lk7_wja:
	s_waitcnt lgkmcnt(0)
	s_barrier
	s_waitcnt lgkmcnt(0)
	v_mfma_f32_16x16x32_bf16 v[64:67], v[148:151], v[180:183], 0
	v_mfma_f32_16x16x32_bf16 v[56:59], v[156:159], v[180:183], 0
	v_mfma_f32_16x16x32_bf16 v[48:51], v[148:151], v[188:191], 0
	v_mfma_f32_16x16x32_bf16 v[40:43], v[156:159], v[188:191], 0
	v_mfma_f32_16x16x32_bf16 v[32:35], v[148:151], v[206:209], 0
	v_mfma_f32_16x16x32_bf16 v[24:27], v[156:159], v[206:209], 0
	v_mfma_f32_16x16x32_bf16 v[16:19], v[148:151], v[214:217], 0
	v_mfma_f32_16x16x32_bf16 v[8:11], v[156:159], v[214:217], 0
	v_mfma_f32_16x16x32_bf16 v[64:67], v[152:155], v[184:187], v[64:67]
	v_mfma_f32_16x16x32_bf16 v[56:59], v[160:163], v[184:187], v[56:59]
	v_mfma_f32_16x16x32_bf16 v[48:51], v[152:155], v[192:195], v[48:51]
	v_mfma_f32_16x16x32_bf16 v[40:43], v[160:163], v[192:195], v[40:43]
	v_mfma_f32_16x16x32_bf16 v[32:35], v[152:155], v[210:213], v[32:35]
	v_mfma_f32_16x16x32_bf16 v[24:27], v[160:163], v[210:213], v[24:27]
	v_mfma_f32_16x16x32_bf16 v[16:19], v[152:155], v[218:221], v[16:19]
	v_mfma_f32_16x16x32_bf16 v[8:11], v[160:163], v[218:221], v[8:11]
	v_mfma_f32_16x16x32_bf16 v[60:63], v[164:167], v[180:183], 0
	v_mfma_f32_16x16x32_bf16 v[52:55], v[172:175], v[180:183], 0
	v_mfma_f32_16x16x32_bf16 v[44:47], v[164:167], v[188:191], 0
	v_mfma_f32_16x16x32_bf16 v[36:39], v[172:175], v[188:191], 0
	v_mfma_f32_16x16x32_bf16 v[28:31], v[164:167], v[206:209], 0
	v_mfma_f32_16x16x32_bf16 v[20:23], v[172:175], v[206:209], 0
	v_mfma_f32_16x16x32_bf16 v[12:15], v[164:167], v[214:217], 0
	v_mfma_f32_16x16x32_bf16 v[4:7], v[172:175], v[214:217], 0
	v_mfma_f32_16x16x32_bf16 v[60:63], v[168:171], v[184:187], v[60:63]
	v_mfma_f32_16x16x32_bf16 v[52:55], v[176:179], v[184:187], v[52:55]
	v_mfma_f32_16x16x32_bf16 v[44:47], v[168:171], v[192:195], v[44:47]
	v_mfma_f32_16x16x32_bf16 v[36:39], v[176:179], v[192:195], v[36:39]
	v_mfma_f32_16x16x32_bf16 v[28:31], v[168:171], v[210:213], v[28:31]
	v_mfma_f32_16x16x32_bf16 v[20:23], v[176:179], v[210:213], v[20:23]
	v_mfma_f32_16x16x32_bf16 v[12:15], v[168:171], v[218:221], v[12:15]
	v_mfma_f32_16x16x32_bf16 v[4:7], v[176:179], v[218:221], v[4:7]
	s_barrier
	s_add_i32 s63, 0, 0x18000
	v_add_u32_e32 v147, s63, v145
	s_add_i32 s64, 0, 0x1c000
	ds_read_b128 v[148:151], v147
	ds_read_b128 v[152:155], v147 offset:1024
	ds_read_b128 v[156:159], v147 offset:2048
	ds_read_b128 v[160:163], v147 offset:3072
	v_add_u32_e32 v147, s64, v145
	ds_read_b128 v[164:167], v147
	ds_read_b128 v[168:171], v147 offset:1024
	ds_read_b128 v[172:175], v147 offset:2048
	ds_read_b128 v[176:179], v147 offset:3072
	s_add_u32 s34, s34, 0x40000
	s_addc_u32 s35, s35, 0
	s_mov_b32 m0, s47
	v_lshl_add_u64 v[242:243], s[34:35], 0, v[136:137]
	ds_read_b128 v[180:183], v146 offset:32768
	ds_read_b128 v[184:187], v146 offset:33792
	ds_read_b128 v[188:191], v146 offset:34816
	ds_read_b128 v[192:195], v146 offset:35840
	ds_read_b128 v[206:209], v146 offset:36864
	ds_read_b128 v[210:213], v146 offset:37888
	ds_read_b128 v[214:217], v146 offset:38912
	ds_read_b128 v[218:221], v146 offset:39936
	global_load_lds_dwordx4 v[242:243], off
	v_lshl_add_u64 v[242:243], s[34:35], 0, v[134:135]
	s_mov_b32 m0, s48
	s_nop 0
	global_load_lds_dwordx4 v[242:243], off
	s_waitcnt vmcnt(8)
	s_waitcnt lgkmcnt(0)
	s_barrier
	s_waitcnt lgkmcnt(0)
	v_mfma_f32_16x16x32_bf16 v[128:131], v[148:151], v[180:183], v[128:131]
	v_mfma_f32_16x16x32_bf16 v[120:123], v[156:159], v[180:183], v[120:123]
	v_mfma_f32_16x16x32_bf16 v[112:115], v[148:151], v[188:191], v[112:115]
	v_mfma_f32_16x16x32_bf16 v[104:107], v[156:159], v[188:191], v[104:107]
	v_mfma_f32_16x16x32_bf16 v[96:99], v[148:151], v[206:209], v[96:99]
	v_mfma_f32_16x16x32_bf16 v[88:91], v[156:159], v[206:209], v[88:91]
	v_mfma_f32_16x16x32_bf16 v[80:83], v[148:151], v[214:217], v[80:83]
	v_mfma_f32_16x16x32_bf16 v[72:75], v[156:159], v[214:217], v[72:75]
	v_mfma_f32_16x16x32_bf16 v[128:131], v[152:155], v[184:187], v[128:131]
	v_mfma_f32_16x16x32_bf16 v[120:123], v[160:163], v[184:187], v[120:123]
	v_mfma_f32_16x16x32_bf16 v[112:115], v[152:155], v[192:195], v[112:115]
	v_mfma_f32_16x16x32_bf16 v[104:107], v[160:163], v[192:195], v[104:107]
	v_mfma_f32_16x16x32_bf16 v[96:99], v[152:155], v[210:213], v[96:99]
	v_mfma_f32_16x16x32_bf16 v[88:91], v[160:163], v[210:213], v[88:91]
	v_mfma_f32_16x16x32_bf16 v[80:83], v[152:155], v[218:221], v[80:83]
	v_mfma_f32_16x16x32_bf16 v[72:75], v[160:163], v[218:221], v[72:75]
	v_mfma_f32_16x16x32_bf16 v[124:127], v[164:167], v[180:183], v[124:127]
	v_mfma_f32_16x16x32_bf16 v[116:119], v[172:175], v[180:183], v[116:119]
	v_mfma_f32_16x16x32_bf16 v[108:111], v[164:167], v[188:191], v[108:111]
	v_mfma_f32_16x16x32_bf16 v[100:103], v[172:175], v[188:191], v[100:103]
	v_mfma_f32_16x16x32_bf16 v[92:95], v[164:167], v[206:209], v[92:95]
	v_mfma_f32_16x16x32_bf16 v[84:87], v[172:175], v[206:209], v[84:87]
	v_mfma_f32_16x16x32_bf16 v[76:79], v[164:167], v[214:217], v[76:79]
	v_mfma_f32_16x16x32_bf16 v[68:71], v[172:175], v[214:217], v[68:71]
	v_mfma_f32_16x16x32_bf16 v[124:127], v[168:171], v[184:187], v[124:127]
	v_mfma_f32_16x16x32_bf16 v[116:119], v[176:179], v[184:187], v[116:119]
	v_mfma_f32_16x16x32_bf16 v[108:111], v[168:171], v[192:195], v[108:111]
	v_mfma_f32_16x16x32_bf16 v[100:103], v[176:179], v[192:195], v[100:103]
	v_mfma_f32_16x16x32_bf16 v[92:95], v[168:171], v[210:213], v[92:95]
	v_mfma_f32_16x16x32_bf16 v[84:87], v[176:179], v[210:213], v[84:87]
	v_mfma_f32_16x16x32_bf16 v[76:79], v[168:171], v[218:221], v[76:79]
	v_mfma_f32_16x16x32_bf16 v[68:71], v[176:179], v[218:221], v[68:71]
	s_barrier
	s_add_i32 s34, s63, s36
	v_lshl_add_u64 v[142:143], v[142:143], 0, s[96:97]
	s_mov_b32 m0, s34
	ds_read_b128 v[180:183], v146 offset:49152
	ds_read_b128 v[184:187], v146 offset:50176
	ds_read_b128 v[188:191], v146 offset:51200
	ds_read_b128 v[192:195], v146 offset:52224
	ds_read_b128 v[206:209], v146 offset:53248
	ds_read_b128 v[210:213], v146 offset:54272
	ds_read_b128 v[214:217], v146 offset:55296
	ds_read_b128 v[218:221], v146 offset:56320
	global_load_lds_dwordx4 v[142:143], off
	s_add_i32 m0, s34, 0x2000
	s_add_u32 s30, s30, 0x40080
	v_lshl_add_u64 v[142:143], v[236:237], 0, s[96:97]
	s_addc_u32 s31, s31, 0
	s_add_i32 s34, s64, s36
	global_load_lds_dwordx4 v[142:143], off
	v_lshl_add_u64 v[142:143], s[30:31], 0, v[2:3]
	s_mov_b32 m0, s34
	s_nop 0
	global_load_lds_dwordx4 v[142:143], off
	v_lshl_add_u64 v[142:143], s[30:31], 0, v[132:133]
	s_add_i32 m0, s34, 0x2000
	s_nop 0
	global_load_lds_dwordx4 v[142:143], off
	v_lshl_add_u64 v[142:143], v[238:239], 0, s[96:97]
	s_mov_b32 m0, s51
	s_nop 0
	global_load_lds_dwordx4 v[142:143], off
	v_lshl_add_u64 v[142:143], v[240:241], 0, s[96:97]
	s_mov_b32 m0, s52
	s_nop 0
	global_load_lds_dwordx4 v[142:143], off
	s_waitcnt vmcnt(8)
	s_waitcnt lgkmcnt(0)
	s_barrier
	s_waitcnt lgkmcnt(0)
	v_mfma_f32_16x16x32_bf16 v[64:67], v[148:151], v[180:183], v[64:67]
	v_mfma_f32_16x16x32_bf16 v[56:59], v[156:159], v[180:183], v[56:59]
	v_mfma_f32_16x16x32_bf16 v[48:51], v[148:151], v[188:191], v[48:51]
	v_mfma_f32_16x16x32_bf16 v[40:43], v[156:159], v[188:191], v[40:43]
	v_mfma_f32_16x16x32_bf16 v[32:35], v[148:151], v[206:209], v[32:35]
	v_mfma_f32_16x16x32_bf16 v[24:27], v[156:159], v[206:209], v[24:27]
	v_mfma_f32_16x16x32_bf16 v[16:19], v[148:151], v[214:217], v[16:19]
	v_mfma_f32_16x16x32_bf16 v[8:11], v[156:159], v[214:217], v[8:11]
	v_mfma_f32_16x16x32_bf16 v[64:67], v[152:155], v[184:187], v[64:67]
	v_mfma_f32_16x16x32_bf16 v[56:59], v[160:163], v[184:187], v[56:59]
	v_mfma_f32_16x16x32_bf16 v[48:51], v[152:155], v[192:195], v[48:51]
	v_mfma_f32_16x16x32_bf16 v[40:43], v[160:163], v[192:195], v[40:43]
	v_mfma_f32_16x16x32_bf16 v[32:35], v[152:155], v[210:213], v[32:35]
	v_mfma_f32_16x16x32_bf16 v[24:27], v[160:163], v[210:213], v[24:27]
	v_mfma_f32_16x16x32_bf16 v[16:19], v[152:155], v[218:221], v[16:19]
	v_mfma_f32_16x16x32_bf16 v[8:11], v[160:163], v[218:221], v[8:11]
	v_mfma_f32_16x16x32_bf16 v[60:63], v[164:167], v[180:183], v[60:63]
	v_mfma_f32_16x16x32_bf16 v[52:55], v[172:175], v[180:183], v[52:55]
	v_mfma_f32_16x16x32_bf16 v[44:47], v[164:167], v[188:191], v[44:47]
	v_mfma_f32_16x16x32_bf16 v[36:39], v[172:175], v[188:191], v[36:39]
	v_mfma_f32_16x16x32_bf16 v[28:31], v[164:167], v[206:209], v[28:31]
	v_mfma_f32_16x16x32_bf16 v[20:23], v[172:175], v[206:209], v[20:23]
	v_mfma_f32_16x16x32_bf16 v[12:15], v[164:167], v[214:217], v[12:15]
	v_mfma_f32_16x16x32_bf16 v[4:7], v[172:175], v[214:217], v[4:7]
	v_mfma_f32_16x16x32_bf16 v[60:63], v[168:171], v[184:187], v[60:63]
	v_mfma_f32_16x16x32_bf16 v[52:55], v[176:179], v[184:187], v[52:55]
	v_mfma_f32_16x16x32_bf16 v[44:47], v[168:171], v[192:195], v[44:47]
	v_mfma_f32_16x16x32_bf16 v[36:39], v[176:179], v[192:195], v[36:39]
	v_mfma_f32_16x16x32_bf16 v[28:31], v[168:171], v[210:213], v[28:31]
	v_mfma_f32_16x16x32_bf16 v[20:23], v[176:179], v[210:213], v[20:23]
	v_mfma_f32_16x16x32_bf16 v[12:15], v[168:171], v[218:221], v[12:15]
	v_mfma_f32_16x16x32_bf16 v[4:7], v[176:179], v[218:221], v[4:7]
	s_barrier
	s_add_i32 s62, s62, 2
	s_add_u32 s28, s28, 0x100
	s_addc_u32 s29, s29, 0
	s_add_u32 s60, s60, 0x100
	s_addc_u32 s61, s61, 0
	s_cmp_gt_u32 s62, 13

.LBB0_319:
	s_mov_b32 s23, 1
	s_nop 0
	v_writelane_b32 v255, s23, 61
	v_mov_b32_e32 v142, v1
	v_mov_b32_e32 v143, v144
	s_lshl_b32 s23, s57, 8
	v_lshl_add_u32 v143, v143, 4, v142
